# EpiGU: row-statistic / shift / output bases taken from SGPRs kept by the phase prologue instead of a scalar kernarg load at the epilogue head
# baseline (speedup 1.0000x reference)
; __device__ __forceinline__ void load_rstd8(const float* ssq, const float* ssqc, int row0, int fq, float (&rs)[2][4]) {
;     const bool isc = row0 >= ML;
; #pragma unroll
;     for (int ai = 0; ai < 2; ++ai)
; #pragma unroll
;         for (int m = 0; m < 4; ++m) {
;             const int row = row0 + ai * HALF + m * 16;
;             float s;
;             if (!isc) { const f32x4 a = *(const f32x4*)(ssq + ((size_t)(2 * fq) * MT + row) * 4), b = *(const f32x4*)(ssq + ((size_t)(2 * fq + 1) * MT + row) * 4);
;                 s = ((a[0] + a[1]) + (a[2] + a[3])) + ((b[0] + b[1]) + (b[2] + b[3])); }
;             else { s = 0.f;
; #pragma unroll
;                 for (int j = 0; j < 8; ++j) s += ssqc[(size_t)(fq * 8 + j) * MC + (row - ML)]; }
;             s += __shfl_xor(s, 16); s += __shfl_xor(s, 32);
;             rs[ai][m] = 1.0f / sqrtf(s * (1.0f / D) + EPS);
;     __device__ __forceinline__ void operator()(const f32x4 (&acc)[2][2][4][2], const Unit& u, int wr, int wc, int fr_, int fq_) const {
;     ...
;         const int row0 = u.pm * BM + wr * 64 + fr, v = vec_of_panel(u.pm);
;         float rs[2][4]; load_rstd8(ssq, ssqc, row0, fq, rs);
;         const int colb = u.pn * BM + wc * 32 + 8 * fq;
;         f32x4 sh[2][2];
; #pragma unroll
;         for (int bj = 0; bj < 2; ++bj)
; #pragma unroll
;             for (int n = 0; n < 2; ++n) sh[bj][n] = *(const f32x4*)(shw + (size_t)v * GU + colb + bj * HALF + 4 * n);
.LBB0_1161:
	s_lshl_b32 s53, s80, 8
	s_add_u32 s53, s53, s81
	v_add_u32_e32 v0, s53, v183
	s_add_u32 s62, s44, 0xf9900000
	s_addc_u32 s63, s45, -1
	s_lshl_b32 s55, s78, 8
	s_add_u32 s55, s55, s86
	v_lshl_add_u32 v186, v185, 3, s55
	v_lshlrev_b32_e32 v186, 2, v186
	s_lshl_b32 s73, s78, 7
	s_add_u32 s73, s73, s86
	v_lshl_add_u32 v192, v185, 3, s73
	s_mov_b32 s74, 0x1600
	v_mul_lo_u32 v188, v0, s74
	v_add_u32_e32 v188, v188, v192
	v_lshlrev_b32_e32 v188, 1, v188
	v_xor_b32_e32 v189, 16, v201
	v_lshlrev_b32_e32 v189, 2, v189
	v_xor_b32_e32 v190, 32, v201
	v_lshlrev_b32_e32 v190, 2, v190
	s_cmp_ge_u32 s80, 16
	s_cselect_b32 s73, 1, 0
	s_cmp_ge_u32 s80, 32
	s_cselect_b32 s73, 2, s73
	s_add_u32 s12, s62, 0xf8a0000
	s_addc_u32 s13, s63, 0
	s_add_u32 s84, s62, 0x15bde000
	s_addc_u32 s85, s63, 0
	s_mul_i32 s74, s76, 0x21000
	s_mul_i32 s73, s73, 0xb000
	s_add_u32 s74, s74, s73
	s_add_u32 s84, s84, s74
	s_addc_u32 s85, s85, 0
	s_cmp_ge_u32 s80, 32
	s_cbranch_scc1 .Lepigu_ctx
	v_mul_u32_u24_e32 v192, 0x4400, v185
	v_add_u32_e32 v192, v192, v0
	v_lshlrev_b32_e32 v182, 4, v192
	v_add_u32_e32 v184, 0x22000, v182
	global_load_dwordx4 v[202:205], v182, s[44:45]
	global_load_dwordx4 v[206:209], v184, s[44:45]
	global_load_dwordx4 v[210:213], v182, s[44:45] offset:256
	global_load_dwordx4 v[214:217], v184, s[44:45] offset:256
	global_load_dwordx4 v[218:221], v182, s[44:45] offset:512
	global_load_dwordx4 v[222:225], v184, s[44:45] offset:512
	global_load_dwordx4 v[228:231], v182, s[44:45] offset:768
	global_load_dwordx4 v[232:235], v184, s[44:45] offset:768
	global_load_dwordx4 v[158:161], v182, s[44:45] offset:2048
	global_load_dwordx4 v[162:165], v184, s[44:45] offset:2048
	global_load_dwordx4 v[166:169], v182, s[44:45] offset:2304
	global_load_dwordx4 v[170:173], v184, s[44:45] offset:2304
	global_load_dwordx4 v[174:177], v182, s[44:45] offset:2560
	global_load_dwordx4 v[178:181], v184, s[44:45] offset:2560
	global_load_dwordx4 v[130:133], v182, s[44:45] offset:2816
	global_load_dwordx4 v[134:137], v184, s[44:45] offset:2816
	global_load_dwordx4 v[138:141], v186, s[84:85]
	global_load_dwordx4 v[142:145], v186, s[84:85] offset:16
	global_load_dwordx4 v[240:243], v186, s[84:85] offset:512
	global_load_dwordx4 v[244:247], v186, s[84:85] offset:528
	s_waitcnt vmcnt(19)
	v_add_f32_e32 v202, v202, v203
	v_add_f32_e32 v204, v204, v205
	s_waitcnt vmcnt(18)
	v_add_f32_e32 v206, v206, v207
	v_add_f32_e32 v208, v208, v209
	v_add_f32_e32 v202, v202, v204
	v_add_f32_e32 v206, v206, v208
	v_add_f32_e32 v202, v202, v206
	s_waitcnt vmcnt(17)
	v_add_f32_e32 v210, v210, v211
	v_add_f32_e32 v212, v212, v213
	s_waitcnt vmcnt(16)
	v_add_f32_e32 v214, v214, v215
	v_add_f32_e32 v216, v216, v217
	v_add_f32_e32 v210, v210, v212
	v_add_f32_e32 v214, v214, v216
	v_add_f32_e32 v210, v210, v214
	s_waitcnt vmcnt(15)
	v_add_f32_e32 v218, v218, v219
	v_add_f32_e32 v220, v220, v221
	s_waitcnt vmcnt(14)
	v_add_f32_e32 v222, v222, v223
	v_add_f32_e32 v224, v224, v225
	v_add_f32_e32 v218, v218, v220
	v_add_f32_e32 v222, v222, v224
	v_add_f32_e32 v218, v218, v222
	s_waitcnt vmcnt(13)
	v_add_f32_e32 v228, v228, v229
	v_add_f32_e32 v230, v230, v231
	s_waitcnt vmcnt(12)
	v_add_f32_e32 v232, v232, v233
	v_add_f32_e32 v234, v234, v235
	v_add_f32_e32 v228, v228, v230
	v_add_f32_e32 v232, v232, v234
	v_add_f32_e32 v228, v228, v232
	s_waitcnt vmcnt(11)
	v_add_f32_e32 v158, v158, v159
	v_add_f32_e32 v160, v160, v161
	s_waitcnt vmcnt(10)
	v_add_f32_e32 v162, v162, v163
	v_add_f32_e32 v164, v164, v165
	v_add_f32_e32 v158, v158, v160
	v_add_f32_e32 v162, v162, v164
	v_add_f32_e32 v158, v158, v162
	s_waitcnt vmcnt(9)
	v_add_f32_e32 v166, v166, v167
	v_add_f32_e32 v168, v168, v169
	s_waitcnt vmcnt(8)
	v_add_f32_e32 v170, v170, v171
	v_add_f32_e32 v172, v172, v173
	v_add_f32_e32 v166, v166, v168
	v_add_f32_e32 v170, v170, v172
	v_add_f32_e32 v166, v166, v170
	s_waitcnt vmcnt(7)
	v_add_f32_e32 v174, v174, v175
	v_add_f32_e32 v176, v176, v177
	s_waitcnt vmcnt(6)
	v_add_f32_e32 v178, v178, v179
	v_add_f32_e32 v180, v180, v181
	v_add_f32_e32 v174, v174, v176
	v_add_f32_e32 v178, v178, v180
	v_add_f32_e32 v174, v174, v178
	s_waitcnt vmcnt(5)
	v_add_f32_e32 v130, v130, v131
	v_add_f32_e32 v132, v132, v133
	s_waitcnt vmcnt(4)
	v_add_f32_e32 v134, v134, v135
	v_add_f32_e32 v136, v136, v137
	v_add_f32_e32 v130, v130, v132
	v_add_f32_e32 v134, v134, v136
	v_add_f32_e32 v130, v130, v134
	s_branch .Lepigu_join
; __device__ __forceinline__ void load_rstd8(const float* ssq, const float* ssqc, int row0, int fq, float (&rs)[2][4]) {
;     ...
;             else { s = 0.f;
; #pragma unroll
;                 for (int j = 0; j < 8; ++j) s += ssqc[(size_t)(fq * 8 + j) * MC + (row - ML)]; }
.Lepigu_ctx:
	v_mul_u32_u24_e32 v192, 0x1000, v185
	v_add_u32_e32 v192, v192, v0
	v_add_u32_e32 v192, 0xffffe000, v192
	v_lshlrev_b32_e32 v182, 2, v192
	v_add_u32_e32 v184, 0x1000, v182
	v_add_u32_e32 v194, 0x2000, v182
	v_add_u32_e32 v196, 0x3000, v182
	global_load_dword v202, v182, s[46:47]
	global_load_dword v203, v182, s[46:47] offset:2048
	global_load_dword v204, v184, s[46:47]
	global_load_dword v205, v184, s[46:47] offset:2048
	global_load_dword v206, v194, s[46:47]
	global_load_dword v207, v194, s[46:47] offset:2048
	global_load_dword v208, v196, s[46:47]
	global_load_dword v209, v196, s[46:47] offset:2048
	global_load_dword v210, v182, s[46:47] offset:64
	global_load_dword v211, v182, s[46:47] offset:2112
	global_load_dword v212, v184, s[46:47] offset:64
	global_load_dword v213, v184, s[46:47] offset:2112
	global_load_dword v214, v194, s[46:47] offset:64
	global_load_dword v215, v194, s[46:47] offset:2112
	global_load_dword v216, v196, s[46:47] offset:64
	global_load_dword v217, v196, s[46:47] offset:2112
	global_load_dword v218, v182, s[46:47] offset:128
	global_load_dword v219, v182, s[46:47] offset:2176
	global_load_dword v220, v184, s[46:47] offset:128
	global_load_dword v221, v184, s[46:47] offset:2176
	global_load_dword v222, v194, s[46:47] offset:128
	global_load_dword v223, v194, s[46:47] offset:2176
	global_load_dword v224, v196, s[46:47] offset:128
	global_load_dword v225, v196, s[46:47] offset:2176
	global_load_dword v228, v182, s[46:47] offset:192
	global_load_dword v229, v182, s[46:47] offset:2240
	global_load_dword v230, v184, s[46:47] offset:192
	global_load_dword v231, v184, s[46:47] offset:2240
	global_load_dword v232, v194, s[46:47] offset:192
	global_load_dword v233, v194, s[46:47] offset:2240
	global_load_dword v234, v196, s[46:47] offset:192
	global_load_dword v235, v196, s[46:47] offset:2240
	global_load_dword v158, v182, s[46:47] offset:512
	global_load_dword v159, v182, s[46:47] offset:2560
	global_load_dword v160, v184, s[46:47] offset:512
	global_load_dword v161, v184, s[46:47] offset:2560
	global_load_dword v162, v194, s[46:47] offset:512
	global_load_dword v163, v194, s[46:47] offset:2560
	global_load_dword v164, v196, s[46:47] offset:512
	global_load_dword v165, v196, s[46:47] offset:2560
	global_load_dword v166, v182, s[46:47] offset:576
	global_load_dword v167, v182, s[46:47] offset:2624
	global_load_dword v168, v184, s[46:47] offset:576
	global_load_dword v169, v184, s[46:47] offset:2624
	global_load_dword v170, v194, s[46:47] offset:576
	global_load_dword v171, v194, s[46:47] offset:2624
	global_load_dword v172, v196, s[46:47] offset:576
	global_load_dword v173, v196, s[46:47] offset:2624
	global_load_dword v174, v182, s[46:47] offset:640
	global_load_dword v175, v182, s[46:47] offset:2688
	global_load_dword v176, v184, s[46:47] offset:640
	global_load_dword v177, v184, s[46:47] offset:2688
	global_load_dword v178, v194, s[46:47] offset:640
	global_load_dword v179, v194, s[46:47] offset:2688
	global_load_dword v180, v196, s[46:47] offset:640
	global_load_dword v181, v196, s[46:47] offset:2688
	global_load_dword v130, v182, s[46:47] offset:704
	global_load_dword v131, v182, s[46:47] offset:2752
	global_load_dword v132, v184, s[46:47] offset:704
	global_load_dword v133, v184, s[46:47] offset:2752
	global_load_dword v134, v194, s[46:47] offset:704
	global_load_dword v135, v194, s[46:47] offset:2752
	global_load_dword v136, v196, s[46:47] offset:704
	global_load_dword v137, v196, s[46:47] offset:2752
	global_load_dwordx4 v[138:141], v186, s[84:85]
	global_load_dwordx4 v[142:145], v186, s[84:85] offset:16
	global_load_dwordx4 v[240:243], v186, s[84:85] offset:512
	global_load_dwordx4 v[244:247], v186, s[84:85] offset:528
	s_waitcnt vmcnt(63)
	v_add_f32_e32 v202, v202, v203
	v_add_f32_e32 v202, v202, v204
	v_add_f32_e32 v202, v202, v205
	v_add_f32_e32 v202, v202, v206
	s_waitcnt vmcnt(62)
	v_add_f32_e32 v202, v202, v207
	s_waitcnt vmcnt(61)
	v_add_f32_e32 v202, v202, v208
	s_waitcnt vmcnt(60)
	v_add_f32_e32 v202, v202, v209
	s_waitcnt vmcnt(58)
	v_add_f32_e32 v210, v210, v211
	s_waitcnt vmcnt(57)
	v_add_f32_e32 v210, v210, v212
	s_waitcnt vmcnt(56)
	v_add_f32_e32 v210, v210, v213
	s_waitcnt vmcnt(55)
	v_add_f32_e32 v210, v210, v214
	s_waitcnt vmcnt(54)
	v_add_f32_e32 v210, v210, v215
	s_waitcnt vmcnt(53)
	v_add_f32_e32 v210, v210, v216
	s_waitcnt vmcnt(52)
	v_add_f32_e32 v210, v210, v217
	s_waitcnt vmcnt(50)
	v_add_f32_e32 v218, v218, v219
	s_waitcnt vmcnt(49)
	v_add_f32_e32 v218, v218, v220
	s_waitcnt vmcnt(48)
	v_add_f32_e32 v218, v218, v221
	s_waitcnt vmcnt(47)
	v_add_f32_e32 v218, v218, v222
	s_waitcnt vmcnt(46)
	v_add_f32_e32 v218, v218, v223
	s_waitcnt vmcnt(45)
	v_add_f32_e32 v218, v218, v224
	s_waitcnt vmcnt(44)
	v_add_f32_e32 v218, v218, v225
	s_waitcnt vmcnt(42)
	v_add_f32_e32 v228, v228, v229
	s_waitcnt vmcnt(41)
	v_add_f32_e32 v228, v228, v230
	s_waitcnt vmcnt(40)
	v_add_f32_e32 v228, v228, v231
	s_waitcnt vmcnt(39)
	v_add_f32_e32 v228, v228, v232
	s_waitcnt vmcnt(38)
	v_add_f32_e32 v228, v228, v233
	s_waitcnt vmcnt(37)
	v_add_f32_e32 v228, v228, v234
	s_waitcnt vmcnt(36)
	v_add_f32_e32 v228, v228, v235
	s_waitcnt vmcnt(34)
	v_add_f32_e32 v158, v158, v159
	s_waitcnt vmcnt(33)
	v_add_f32_e32 v158, v158, v160
	s_waitcnt vmcnt(32)
	v_add_f32_e32 v158, v158, v161
	s_waitcnt vmcnt(31)
	v_add_f32_e32 v158, v158, v162
	s_waitcnt vmcnt(30)
	v_add_f32_e32 v158, v158, v163
	s_waitcnt vmcnt(29)
	v_add_f32_e32 v158, v158, v164
	s_waitcnt vmcnt(28)
	v_add_f32_e32 v158, v158, v165
	s_waitcnt vmcnt(26)
	v_add_f32_e32 v166, v166, v167
	s_waitcnt vmcnt(25)
	v_add_f32_e32 v166, v166, v168
	s_waitcnt vmcnt(24)
	v_add_f32_e32 v166, v166, v169
	s_waitcnt vmcnt(23)
	v_add_f32_e32 v166, v166, v170
	s_waitcnt vmcnt(22)
	v_add_f32_e32 v166, v166, v171
	s_waitcnt vmcnt(21)
	v_add_f32_e32 v166, v166, v172
	s_waitcnt vmcnt(20)
	v_add_f32_e32 v166, v166, v173
	s_waitcnt vmcnt(18)
	v_add_f32_e32 v174, v174, v175
	s_waitcnt vmcnt(17)
	v_add_f32_e32 v174, v174, v176
	s_waitcnt vmcnt(16)
	v_add_f32_e32 v174, v174, v177
	s_waitcnt vmcnt(15)
	v_add_f32_e32 v174, v174, v178
	s_waitcnt vmcnt(14)
	v_add_f32_e32 v174, v174, v179
	s_waitcnt vmcnt(13)
	v_add_f32_e32 v174, v174, v180
	s_waitcnt vmcnt(12)
	v_add_f32_e32 v174, v174, v181
	s_waitcnt vmcnt(10)
	v_add_f32_e32 v130, v130, v131
	s_waitcnt vmcnt(9)
	v_add_f32_e32 v130, v130, v132
	s_waitcnt vmcnt(8)
	v_add_f32_e32 v130, v130, v133
	s_waitcnt vmcnt(7)
	v_add_f32_e32 v130, v130, v134
	s_waitcnt vmcnt(6)
	v_add_f32_e32 v130, v130, v135
	s_waitcnt vmcnt(5)
	v_add_f32_e32 v130, v130, v136
	s_waitcnt vmcnt(4)
	v_add_f32_e32 v130, v130, v137
